# k-major PV order, row-max chain hoisted into PV MFMA shadows, last three PV MFMAs deferred past the tile barrier, counted PV waits (plus chain + peel in the GEMMs)
# speedup vs baseline: 1.0101x; 1.0018x over previous
.LBB0_1096:
	ds_read_b128 v[64:67], v194 offset:49152
	ds_read_b128 v[68:71], v195 offset:57344
	ds_read_b128 v[214:217], v196 offset:49152
	ds_read_b128 v[224:227], v197 offset:57344
	v_add_f32_e32 v160, 0, v175
	v_add_f32_e32 v160, v223, v160
	s_waitcnt lgkmcnt(3)
	v_mfma_f32_32x32x16_bf16 v[80:95], v[64:67], v[100:103], 0
	v_add_f32_e32 v160, v161, v160
	v_add_f32_e32 v160, v220, v160
	v_add_f32_e32 v160, v162, v160
	v_add_f32_e32 v160, v174, v160
	v_add_f32_e32 v160, v163, v160
	v_add_f32_e32 v160, v173, v160
	v_add_f32_e32 v160, v164, v160
	s_waitcnt lgkmcnt(2)
	v_mfma_f32_32x32x16_bf16 v[64:79], v[68:71], v[100:103], 0
	v_add_f32_e32 v160, v172, v160
	v_add_f32_e32 v160, v165, v160
	v_add_f32_e32 v160, v171, v160
	v_exp_f32_e32 v156, v156
	v_add_f32_e32 v160, v166, v160
	v_exp_f32_e32 v157, v157
	v_add_f32_e32 v160, v170, v160
	s_waitcnt lgkmcnt(1)
	v_mfma_f32_32x32x16_bf16 v[80:95], v[214:217], v[108:111], v[80:95]
	v_exp_f32_e32 v154, v154
	v_add_f32_e32 v160, v167, v160
	v_exp_f32_e32 v155, v155
	v_add_f32_e32 v160, v169, v160
	v_exp_f32_e32 v148, v148
	v_add_f32_e32 v160, v156, v160
	v_exp_f32_e32 v149, v149
	s_waitcnt lgkmcnt(0)
	v_mfma_f32_32x32x16_bf16 v[64:79], v[224:227], v[108:111], v[64:79]
	ds_read_b128 v[214:217], v198 offset:49152
	ds_read_b128 v[224:227], v200 offset:57344
	v_add_f32_e32 v160, v157, v160
	v_exp_f32_e32 v146, v146
	v_add_f32_e32 v160, v154, v160
	v_exp_f32_e32 v147, v147
	v_add_f32_e32 v160, v155, v160
	v_exp_f32_e32 v144, v144
	s_waitcnt lgkmcnt(1)
	v_mfma_f32_32x32x16_bf16 v[80:95], v[214:217], v[96:99], v[80:95]
	v_add_f32_e32 v160, v148, v160
	v_exp_f32_e32 v145, v145
	v_add_f32_e32 v160, v149, v160
	v_exp_f32_e32 v158, v158
	v_add_f32_e32 v160, v146, v160
	v_exp_f32_e32 v159, v159
	v_add_f32_e32 v160, v147, v160
	s_waitcnt lgkmcnt(0)
	v_mfma_f32_32x32x16_bf16 v[64:79], v[224:227], v[96:99], v[64:79]
	ds_read_b128 v[214:217], v199 offset:49152
	ds_read_b128 v[224:227], v201 offset:57344
	v_exp_f32_e32 v152, v152
	v_add_f32_e32 v160, v144, v160
	v_exp_f32_e32 v153, v153
	v_add_f32_e32 v160, v145, v160
	v_exp_f32_e32 v150, v150
	v_add_f32_e32 v160, v158, v160
	s_waitcnt lgkmcnt(1)
	v_mfma_f32_32x32x16_bf16 v[80:95], v[214:217], v[104:107], v[80:95]
	v_exp_f32_e32 v151, v151
	v_add_f32_e32 v160, v159, v160
	v_add_f32_e32 v160, v152, v160
	v_add_f32_e32 v160, v153, v160
	v_add_f32_e32 v160, v150, v160
	v_add_f32_e32 v211, v151, v160
	v_mov_b32_e32 v218, v211
	s_waitcnt lgkmcnt(0)
	v_mfma_f32_32x32x16_bf16 v[64:79], v[224:227], v[104:107], v[64:79]
	ds_read_b128 v[214:217], v202 offset:49152
	ds_read_b128 v[224:227], v203 offset:57344
	v_permlane32_swap_b32_e32 v211, v218
	s_waitcnt lgkmcnt(1)
	v_mfma_f32_32x32x16_bf16 v[80:95], v[214:217], v[116:119], v[80:95]
	s_waitcnt lgkmcnt(0)
	v_mfma_f32_32x32x16_bf16 v[64:79], v[224:227], v[116:119], v[64:79]
	ds_read_b128 v[214:217], v204 offset:49152
	ds_read_b128 v[224:227], v205 offset:57344
	s_waitcnt lgkmcnt(1)
	v_mfma_f32_32x32x16_bf16 v[80:95], v[214:217], v[124:127], v[80:95]
	s_waitcnt lgkmcnt(0)
	v_mfma_f32_32x32x16_bf16 v[64:79], v[224:227], v[124:127], v[64:79]
	ds_read_b128 v[214:217], v206 offset:49152
	ds_read_b128 v[224:227], v208 offset:57344
	s_waitcnt lgkmcnt(1)
	v_mfma_f32_32x32x16_bf16 v[80:95], v[214:217], v[112:115], v[80:95]
	s_waitcnt lgkmcnt(0)
	v_mfma_f32_32x32x16_bf16 v[64:79], v[224:227], v[112:115], v[64:79]
	ds_read_b128 v[214:217], v207 offset:49152
	ds_read_b128 v[224:227], v209 offset:57344
	v_cvt_pk_bf16_f32 v160, v175, v223
	v_cvt_pk_bf16_f32 v161, v161, v220
	v_cvt_pk_bf16_f32 v162, v162, v174
	v_cvt_pk_bf16_f32 v163, v163, v173
	v_cvt_pk_bf16_f32 v164, v164, v172
	v_cvt_pk_bf16_f32 v165, v165, v171
	s_waitcnt lgkmcnt(1)
	v_mfma_f32_32x32x16_bf16 v[80:95], v[214:217], v[120:123], v[80:95]
	v_permlane32_swap_b32_e32 v160, v162
	v_cvt_pk_bf16_f32 v166, v166, v170
	v_cvt_pk_bf16_f32 v167, v167, v169
	v_cvt_pk_bf16_f32 v170, v156, v157
	v_cvt_pk_bf16_f32 v171, v154, v155
	v_cvt_pk_bf16_f32 v172, v148, v149
	s_waitcnt lgkmcnt(0)
	v_mfma_f32_32x32x16_bf16 v[64:79], v[224:227], v[120:123], v[64:79]
	v_cvt_pk_bf16_f32 v173, v146, v147
	v_cvt_pk_bf16_f32 v214, v144, v145
	v_cvt_pk_bf16_f32 v215, v158, v159
	v_cvt_pk_bf16_f32 v216, v152, v153
	v_cvt_pk_bf16_f32 v217, v150, v151
	v_permlane32_swap_b32_e32 v161, v163
	v_permlane32_swap_b32_e32 v164, v166
	v_permlane32_swap_b32_e32 v165, v167
	v_permlane32_swap_b32_e32 v170, v172
	v_permlane32_swap_b32_e32 v171, v173
	v_permlane32_swap_b32_e32 v214, v216
	v_permlane32_swap_b32_e32 v215, v217
	v_lshl_add_u64 v[144:145], v[180:181], 0, s[8:9]
	s_mov_b32 s2, 0x322f0000
	v_add_co_u32_e32 v146, vcc, s2, v144
	s_mov_b32 s2, 0x32318000
	s_nop 0
	v_addc_co_u32_e32 v147, vcc, 0, v145, vcc
	v_add_co_u32_e32 v148, vcc, s2, v144
	v_lshl_add_u64 v[152:153], v[178:179], 0, s[8:9]
	s_nop 0
	v_addc_co_u32_e32 v149, vcc, 0, v145, vcc
	s_mov_b32 s2, 0x41018000
	v_add_co_u32_e32 v154, vcc, s2, v152
	s_mov_b32 s2, 0x4101c000
	s_nop 0
	v_addc_co_u32_e32 v155, vcc, 0, v153, vcc
	v_add_co_u32_e32 v156, vcc, s2, v152
	global_load_dwordx4 v[144:147], v[146:147], off offset:2560
	s_nop 0
	global_load_dwordx4 v[148:151], v[148:149], off offset:2560
	v_addc_co_u32_e32 v157, vcc, 0, v153, vcc
	global_load_dwordx4 v[152:155], v[154:155], off
	s_nop 0
	global_load_dwordx4 v[156:159], v[156:157], off
	ds_read_b64_tr_b16 v[220:221], v189 offset:0
	ds_read_b64_tr_b16 v[222:223], v189 offset:0x800
	ds_read_b64_tr_b16 v[224:225], v189 offset:0x200
	ds_read_b64_tr_b16 v[226:227], v189 offset:0xa00
	ds_read_b64_tr_b16 v[230:231], v189 offset:0x400
	ds_read_b64_tr_b16 v[232:233], v189 offset:0xc00
	ds_read_b64_tr_b16 v[238:239], v189 offset:0x600
	ds_read_b64_tr_b16 v[240:241], v189 offset:0xe00
	s_waitcnt lgkmcnt(6)
	s_nop 0
	v_mfma_f32_32x32x16_bf16 v[0:15], v[160:163], v[220:223], v[0:15]
	ds_read_b64_tr_b16 v[220:221], v189 offset:0x1000
	ds_read_b64_tr_b16 v[222:223], v189 offset:0x1800
	s_waitcnt lgkmcnt(6)
	v_mfma_f32_32x32x16_bf16 v[48:63], v[160:163], v[224:227], v[48:63]
	ds_read_b64_tr_b16 v[224:225], v189 offset:0x1200
	ds_read_b64_tr_b16 v[226:227], v189 offset:0x1a00
	s_waitcnt lgkmcnt(6)
	v_mfma_f32_32x32x16_bf16 v[32:47], v[160:163], v[230:233], v[32:47]
	ds_read_b64_tr_b16 v[230:231], v189 offset:0x1400
	ds_read_b64_tr_b16 v[232:233], v189 offset:0x1c00
	s_waitcnt lgkmcnt(6)
	v_mfma_f32_32x32x16_bf16 v[16:31], v[160:163], v[238:241], v[16:31]
	ds_read_b64_tr_b16 v[238:239], v189 offset:0x1600
	ds_read_b64_tr_b16 v[240:241], v189 offset:0x1e00
	s_waitcnt lgkmcnt(6)
	v_mfma_f32_32x32x16_bf16 v[0:15], v[164:167], v[220:223], v[0:15]
	ds_read_b64_tr_b16 v[220:221], v189 offset:0x2000
	ds_read_b64_tr_b16 v[222:223], v189 offset:0x2800
	v_max_f32_e32 v160, v81, v81
	v_max_f32_e32 v161, v80, v80
	v_max_f32_e32 v160, v161, v160
	v_max3_f32 v160, v160, v82, v83
	v_max3_f32 v160, v160, v84, v85
	v_max3_f32 v160, v160, v86, v87
	v_max3_f32 v160, v160, v88, v89
	v_max3_f32 v160, v160, v90, v91
	s_waitcnt lgkmcnt(6)
	v_mfma_f32_32x32x16_bf16 v[48:63], v[164:167], v[224:227], v[48:63]
	ds_read_b64_tr_b16 v[224:225], v189 offset:0x2200
	ds_read_b64_tr_b16 v[226:227], v189 offset:0x2a00
	s_waitcnt lgkmcnt(6)
	v_mfma_f32_32x32x16_bf16 v[32:47], v[164:167], v[230:233], v[32:47]
	ds_read_b64_tr_b16 v[230:231], v189 offset:0x2400
	ds_read_b64_tr_b16 v[232:233], v189 offset:0x2c00
	v_max3_f32 v160, v160, v92, v93
	v_max3_f32 v160, v160, v94, v95
	v_max3_f32 v160, v160, v64, v65
	v_max3_f32 v160, v160, v66, v67
	v_max3_f32 v160, v160, v68, v69
	v_max3_f32 v160, v160, v70, v71
	v_max3_f32 v160, v160, v72, v73
	v_max3_f32 v160, v160, v74, v75
	s_waitcnt lgkmcnt(6)
	v_mfma_f32_32x32x16_bf16 v[16:31], v[164:167], v[238:241], v[16:31]
	ds_read_b64_tr_b16 v[238:239], v189 offset:0x2600
	ds_read_b64_tr_b16 v[240:241], v189 offset:0x2e00
	s_waitcnt lgkmcnt(6)
	v_mfma_f32_32x32x16_bf16 v[0:15], v[170:173], v[220:223], v[0:15]
	ds_read_b64_tr_b16 v[220:221], v189 offset:0x3000
	ds_read_b64_tr_b16 v[222:223], v189 offset:0x3800
	v_max3_f32 v160, v160, v76, v77
	v_max3_f32 v160, v160, v78, v79
	v_mov_b32_e32 v161, v160
	s_nop 1
	v_permlane32_swap_b32_e32 v160, v161
	v_max_f32_e32 v161, v161, v161
	v_max_f32_e32 v160, v160, v160
	v_max_f32_e32 v160, v160, v161
	s_waitcnt lgkmcnt(6)
	v_mfma_f32_32x32x16_bf16 v[48:63], v[170:173], v[224:227], v[48:63]
	ds_read_b64_tr_b16 v[224:225], v189 offset:0x3200
	ds_read_b64_tr_b16 v[226:227], v189 offset:0x3a00
	s_waitcnt lgkmcnt(6)
	v_mfma_f32_32x32x16_bf16 v[32:47], v[170:173], v[230:233], v[32:47]
	ds_read_b64_tr_b16 v[230:231], v189 offset:0x3400
	ds_read_b64_tr_b16 v[232:233], v189 offset:0x3c00
	v_sub_f32_e32 v161, v160, v168
	v_cmp_ge_f32_e32 vcc, s90, v161
	v_max_f32_e32 v161, v168, v168
	v_max_f32_e32 v160, v161, v160
	v_sub_f32_e32 v161, v168, v160
	v_mul_f32_e32 v161, 0x3e0293ee, v161
	v_exp_f32_e32 v161, v161
	s_cmp_eq_u64 vcc, exec
	s_cselect_b64 s[38:39], -1, 0
	s_waitcnt lgkmcnt(6)
	v_mfma_f32_32x32x16_bf16 v[16:31], v[170:173], v[238:241], v[16:31]
	ds_read_b64_tr_b16 v[238:239], v189 offset:0x3600
	ds_read_b64_tr_b16 v[240:241], v189 offset:0x3e00
	s_waitcnt lgkmcnt(6)
	v_mfma_f32_32x32x16_bf16 v[0:15], v[214:217], v[220:223], v[0:15]
	s_waitcnt lgkmcnt(0)
	s_barrier
	v_mfma_f32_32x32x16_bf16 v[48:63], v[214:217], v[224:227], v[48:63]
	s_waitcnt vmcnt(4)
	v_cndmask_b32_e64 v219, v161, 1.0, s[38:39]
	v_cmp_gt_f32_e32 vcc, 1.0, v219
	s_waitcnt vmcnt(7)
	ds_write_b128 v190, v[128:131]
	s_waitcnt vmcnt(6)
	ds_write_b128 v191, v[132:135]
	v_mfma_f32_32x32x16_bf16 v[32:47], v[214:217], v[230:233], v[32:47]
	s_waitcnt vmcnt(5)
	ds_write_b128 v192, v[136:139] offset:32768
	s_waitcnt vmcnt(4)
	ds_write_b128 v193, v[140:143] offset:32768
	v_mfma_f32_32x32x16_bf16 v[16:31], v[214:217], v[238:241], v[16:31]
	s_cbranch_vccz .LBB0_1100
	s_and_saveexec_b64 s[2:3], s[36:37]
	ds_write_b32 v186, v219 offset:128
	s_or_b64 exec, exec, s[2:3]
	s_waitcnt lgkmcnt(0)
	v_add_u32_e32 v161, s27, v185
	ds_read_b128 v[162:165], v161 offset:224
	ds_read_b128 v[170:173], v161 offset:192
	ds_read_b128 v[214:217], v161 offset:160
	ds_read_b128 v[220:223], v161 offset:128
	s_waitcnt lgkmcnt(3)
	v_pk_mul_f32 v[12:13], v[12:13], v[162:163]
	s_waitcnt lgkmcnt(2)
	v_pk_mul_f32 v[8:9], v[8:9], v[170:171]
	s_waitcnt lgkmcnt(1)
	v_pk_mul_f32 v[4:5], v[4:5], v[214:215]
	v_pk_mul_f32 v[14:15], v[14:15], v[164:165]
	v_pk_mul_f32 v[10:11], v[10:11], v[172:173]
	v_pk_mul_f32 v[6:7], v[6:7], v[216:217]
	s_waitcnt lgkmcnt(0)
	v_pk_mul_f32 v[2:3], v[2:3], v[222:223]
	v_pk_mul_f32 v[0:1], v[0:1], v[220:221]
	v_pk_mul_f32 v[60:61], v[60:61], v[162:163]
	v_pk_mul_f32 v[56:57], v[56:57], v[170:171]
	v_pk_mul_f32 v[52:53], v[52:53], v[214:215]
	v_pk_mul_f32 v[62:63], v[62:63], v[164:165]
	v_pk_mul_f32 v[58:59], v[58:59], v[172:173]
	v_pk_mul_f32 v[54:55], v[54:55], v[216:217]
	v_pk_mul_f32 v[50:51], v[50:51], v[222:223]
	v_pk_mul_f32 v[48:49], v[48:49], v[220:221]
	v_pk_mul_f32 v[44:45], v[44:45], v[162:163]
	v_pk_mul_f32 v[40:41], v[40:41], v[170:171]
	v_pk_mul_f32 v[36:37], v[36:37], v[214:215]
	v_pk_mul_f32 v[46:47], v[46:47], v[164:165]
	v_pk_mul_f32 v[42:43], v[42:43], v[172:173]
	v_pk_mul_f32 v[38:39], v[38:39], v[216:217]
	v_pk_mul_f32 v[34:35], v[34:35], v[222:223]
	v_pk_mul_f32 v[32:33], v[32:33], v[220:221]
	v_pk_mul_f32 v[28:29], v[28:29], v[162:163]
	v_pk_mul_f32 v[24:25], v[24:25], v[170:171]
	v_pk_mul_f32 v[20:21], v[20:21], v[214:215]
	v_pk_mul_f32 v[30:31], v[30:31], v[164:165]
	v_pk_mul_f32 v[26:27], v[26:27], v[172:173]
	v_pk_mul_f32 v[22:23], v[22:23], v[216:217]
	v_pk_mul_f32 v[18:19], v[18:19], v[222:223]
	v_pk_mul_f32 v[16:17], v[16:17], v[220:221]

.LBB0_1102:
	ds_read_b64_tr_b16 v[214:215], v188 offset:0
	ds_read_b64_tr_b16 v[216:217], v188 offset:0x800
	ds_read_b64_tr_b16 v[224:225], v188 offset:0x200
	ds_read_b64_tr_b16 v[226:227], v188 offset:0xa00
	ds_read_b64_tr_b16 v[230:231], v188 offset:0x400
	ds_read_b64_tr_b16 v[232:233], v188 offset:0xc00
	ds_read_b64_tr_b16 v[238:239], v188 offset:0x600
	ds_read_b64_tr_b16 v[240:241], v188 offset:0xe00
	s_waitcnt lgkmcnt(6)
	s_nop 0
	v_mfma_f32_32x32x16_bf16 v[0:15], v[160:163], v[214:217], v[0:15]
	ds_read_b64_tr_b16 v[214:215], v188 offset:0x1000
	ds_read_b64_tr_b16 v[216:217], v188 offset:0x1800
	s_waitcnt lgkmcnt(6)
	v_mfma_f32_32x32x16_bf16 v[48:63], v[160:163], v[224:227], v[48:63]
	ds_read_b64_tr_b16 v[224:225], v188 offset:0x1200
	ds_read_b64_tr_b16 v[226:227], v188 offset:0x1a00
	s_waitcnt lgkmcnt(6)
	v_mfma_f32_32x32x16_bf16 v[32:47], v[160:163], v[230:233], v[32:47]
	ds_read_b64_tr_b16 v[230:231], v188 offset:0x1400
	ds_read_b64_tr_b16 v[232:233], v188 offset:0x1c00
	s_waitcnt lgkmcnt(6)
	v_mfma_f32_32x32x16_bf16 v[16:31], v[160:163], v[238:241], v[16:31]
	ds_read_b64_tr_b16 v[238:239], v188 offset:0x1600
	ds_read_b64_tr_b16 v[240:241], v188 offset:0x1e00
	s_waitcnt lgkmcnt(6)
	v_mfma_f32_32x32x16_bf16 v[0:15], v[164:167], v[214:217], v[0:15]
	ds_read_b64_tr_b16 v[214:215], v188 offset:0x2000
	ds_read_b64_tr_b16 v[216:217], v188 offset:0x2800
	v_max_f32_e32 v160, v81, v81
	v_max_f32_e32 v161, v80, v80
	v_max_f32_e32 v160, v161, v160
	v_max3_f32 v160, v160, v82, v83
	v_max3_f32 v160, v160, v84, v85
	v_max3_f32 v160, v160, v86, v87
	v_max3_f32 v160, v160, v88, v89
	v_max3_f32 v160, v160, v90, v91
	s_waitcnt lgkmcnt(6)
	v_mfma_f32_32x32x16_bf16 v[48:63], v[164:167], v[224:227], v[48:63]
	ds_read_b64_tr_b16 v[224:225], v188 offset:0x2200
	ds_read_b64_tr_b16 v[226:227], v188 offset:0x2a00
	s_waitcnt lgkmcnt(6)
	v_mfma_f32_32x32x16_bf16 v[32:47], v[164:167], v[230:233], v[32:47]
	ds_read_b64_tr_b16 v[230:231], v188 offset:0x2400
	ds_read_b64_tr_b16 v[232:233], v188 offset:0x2c00
	v_max3_f32 v160, v160, v92, v93
	v_max3_f32 v160, v160, v94, v95
	v_max3_f32 v160, v160, v64, v65
	v_max3_f32 v160, v160, v66, v67
	v_max3_f32 v160, v160, v68, v69
	v_max3_f32 v160, v160, v70, v71
	v_max3_f32 v160, v160, v72, v73
	v_max3_f32 v160, v160, v74, v75
	s_waitcnt lgkmcnt(6)
	v_mfma_f32_32x32x16_bf16 v[16:31], v[164:167], v[238:241], v[16:31]
	ds_read_b64_tr_b16 v[238:239], v188 offset:0x2600
	ds_read_b64_tr_b16 v[240:241], v188 offset:0x2e00
	s_waitcnt lgkmcnt(6)
	v_mfma_f32_32x32x16_bf16 v[0:15], v[168:171], v[214:217], v[0:15]
	ds_read_b64_tr_b16 v[214:215], v188 offset:0x3000
	ds_read_b64_tr_b16 v[216:217], v188 offset:0x3800
	v_max3_f32 v160, v160, v76, v77
	v_max3_f32 v160, v160, v78, v79
	v_mov_b32_e32 v161, v160
	s_nop 1
	v_permlane32_swap_b32_e32 v160, v161
	v_max_f32_e32 v161, v161, v161
	v_max_f32_e32 v160, v160, v160
	v_max_f32_e32 v160, v160, v161
	s_waitcnt lgkmcnt(6)
	v_mfma_f32_32x32x16_bf16 v[48:63], v[168:171], v[224:227], v[48:63]
	ds_read_b64_tr_b16 v[224:225], v188 offset:0x3200
	ds_read_b64_tr_b16 v[226:227], v188 offset:0x3a00
	s_waitcnt lgkmcnt(6)
	v_mfma_f32_32x32x16_bf16 v[32:47], v[168:171], v[230:233], v[32:47]
	ds_read_b64_tr_b16 v[230:231], v188 offset:0x3400
	ds_read_b64_tr_b16 v[232:233], v188 offset:0x3c00
	v_sub_f32_e32 v161, v160, v220
	v_cmp_ge_f32_e32 vcc, s90, v161
	v_max_f32_e32 v161, v220, v220
	v_max_f32_e32 v161, v161, v160
	v_sub_f32_e32 v160, v220, v161
	v_mul_f32_e32 v160, 0x3e0293ee, v160
	v_exp_f32_e32 v160, v160
	s_cmp_eq_u64 vcc, exec
	s_cselect_b64 s[38:39], -1, 0
	s_waitcnt lgkmcnt(6)
	v_mfma_f32_32x32x16_bf16 v[16:31], v[168:171], v[238:241], v[16:31]
	ds_read_b64_tr_b16 v[238:239], v188 offset:0x3600
	ds_read_b64_tr_b16 v[240:241], v188 offset:0x3e00
	s_waitcnt lgkmcnt(6)
	v_mfma_f32_32x32x16_bf16 v[0:15], v[172:175], v[214:217], v[0:15]
	s_waitcnt lgkmcnt(0)
	s_barrier
	v_mfma_f32_32x32x16_bf16 v[48:63], v[172:175], v[224:227], v[48:63]
	s_waitcnt vmcnt(4)
	v_cndmask_b32_e64 v160, v160, 1.0, s[38:39]
	v_cmp_gt_f32_e32 vcc, 1.0, v160
	s_waitcnt vmcnt(3)
	ds_write_b128 v190, v[144:147] offset:16384
	s_waitcnt vmcnt(2)
	ds_write_b128 v191, v[148:151] offset:16384
	v_mfma_f32_32x32x16_bf16 v[32:47], v[172:175], v[230:233], v[32:47]
	s_waitcnt vmcnt(1)
	ds_write_b128 v192, v[152:155] offset:49152
	s_waitcnt vmcnt(0)
	ds_write_b128 v193, v[156:159] offset:49152
	v_mfma_f32_32x32x16_bf16 v[16:31], v[172:175], v[238:241], v[16:31]
	s_cbranch_vccz .LBB0_1106
	s_and_saveexec_b64 s[2:3], s[36:37]
	ds_write_b32 v186, v160 offset:128
	s_or_b64 exec, exec, s[2:3]
	s_waitcnt lgkmcnt(0)
	v_add_u32_e32 v156, s27, v185
	ds_read_b128 v[144:147], v156 offset:224
	ds_read_b128 v[148:151], v156 offset:192
	ds_read_b128 v[152:155], v156 offset:160
	ds_read_b128 v[156:159], v156 offset:128
	s_waitcnt lgkmcnt(3)
	v_pk_mul_f32 v[12:13], v[12:13], v[144:145]
	s_waitcnt lgkmcnt(2)
	v_pk_mul_f32 v[8:9], v[8:9], v[148:149]
	s_waitcnt lgkmcnt(1)
	v_pk_mul_f32 v[4:5], v[4:5], v[152:153]
	v_pk_mul_f32 v[14:15], v[14:15], v[146:147]
	v_pk_mul_f32 v[10:11], v[10:11], v[150:151]
	v_pk_mul_f32 v[6:7], v[6:7], v[154:155]
	s_waitcnt lgkmcnt(0)
	v_pk_mul_f32 v[2:3], v[2:3], v[158:159]
	v_pk_mul_f32 v[0:1], v[0:1], v[156:157]
	v_pk_mul_f32 v[60:61], v[60:61], v[144:145]
	v_pk_mul_f32 v[56:57], v[56:57], v[148:149]
	v_pk_mul_f32 v[52:53], v[52:53], v[152:153]
	v_pk_mul_f32 v[62:63], v[62:63], v[146:147]
	v_pk_mul_f32 v[58:59], v[58:59], v[150:151]
	v_pk_mul_f32 v[54:55], v[54:55], v[154:155]
	v_pk_mul_f32 v[50:51], v[50:51], v[158:159]
	v_pk_mul_f32 v[48:49], v[48:49], v[156:157]
	v_pk_mul_f32 v[44:45], v[44:45], v[144:145]
	v_pk_mul_f32 v[40:41], v[40:41], v[148:149]
	v_pk_mul_f32 v[36:37], v[36:37], v[152:153]
	v_pk_mul_f32 v[46:47], v[46:47], v[146:147]
	v_pk_mul_f32 v[42:43], v[42:43], v[150:151]
	v_pk_mul_f32 v[38:39], v[38:39], v[154:155]
	v_pk_mul_f32 v[34:35], v[34:35], v[158:159]
	v_pk_mul_f32 v[32:33], v[32:33], v[156:157]
	v_pk_mul_f32 v[28:29], v[28:29], v[144:145]
	v_pk_mul_f32 v[24:25], v[24:25], v[148:149]
	v_pk_mul_f32 v[20:21], v[20:21], v[152:153]
	v_pk_mul_f32 v[30:31], v[30:31], v[146:147]
	v_pk_mul_f32 v[26:27], v[26:27], v[150:151]
	v_pk_mul_f32 v[22:23], v[22:23], v[154:155]
	v_pk_mul_f32 v[18:19], v[18:19], v[158:159]
	v_pk_mul_f32 v[16:17], v[16:17], v[156:157]

.LBB0_1135:
	ds_read_b128 v[64:67], v194 offset:57344
	ds_read_b128 v[68:71], v212 offset:57344
	ds_read_b128 v[214:217], v197 offset:57344
	ds_read_b128 v[230:233], v211 offset:57344
	v_add_f32_e32 v164, 0, v165
	v_add_f32_e32 v164, v224, v164
	s_waitcnt lgkmcnt(3)
	v_mfma_f32_32x32x16_bf16 v[80:95], v[64:67], v[140:143], 0
	v_add_f32_e32 v164, v166, v164
	v_add_f32_e32 v164, v225, v164
	v_add_f32_e32 v164, v223, v164
	v_add_f32_e32 v164, v226, v164
	v_add_f32_e32 v164, v167, v164
	v_add_f32_e32 v164, v222, v164
	v_add_f32_e32 v164, v172, v164
	s_waitcnt lgkmcnt(2)
	v_mfma_f32_32x32x16_bf16 v[64:79], v[68:71], v[140:143], 0
	v_add_f32_e32 v164, v174, v164
	v_add_f32_e32 v164, v173, v164
	v_add_f32_e32 v164, v175, v164
	v_exp_f32_e32 v158, v158
	v_add_f32_e32 v164, v160, v164
	v_exp_f32_e32 v159, v159
	v_add_f32_e32 v164, v162, v164
	s_waitcnt lgkmcnt(1)
	v_mfma_f32_32x32x16_bf16 v[80:95], v[214:217], v[136:139], v[80:95]
	v_exp_f32_e32 v156, v156
	v_add_f32_e32 v164, v161, v164
	v_exp_f32_e32 v157, v157
	v_add_f32_e32 v164, v163, v164
	v_exp_f32_e32 v152, v152
	v_add_f32_e32 v164, v158, v164
	v_exp_f32_e32 v153, v153
	s_waitcnt lgkmcnt(0)
	v_mfma_f32_32x32x16_bf16 v[64:79], v[230:233], v[136:139], v[64:79]
	ds_read_b128 v[214:217], v196 offset:57344
	ds_read_b128 v[230:233], v210 offset:57344
	v_add_f32_e32 v164, v159, v164
	v_exp_f32_e32 v148, v148
	v_add_f32_e32 v164, v156, v164
	v_exp_f32_e32 v149, v149
	v_add_f32_e32 v164, v157, v164
	v_exp_f32_e32 v146, v146
	s_waitcnt lgkmcnt(1)
	v_mfma_f32_32x32x16_bf16 v[80:95], v[214:217], v[132:135], v[80:95]
	v_add_f32_e32 v164, v152, v164
	v_exp_f32_e32 v147, v147
	v_add_f32_e32 v164, v153, v164
	v_exp_f32_e32 v154, v154
	v_add_f32_e32 v164, v148, v164
	v_exp_f32_e32 v155, v155
	v_add_f32_e32 v164, v149, v164
	s_waitcnt lgkmcnt(0)
	v_mfma_f32_32x32x16_bf16 v[64:79], v[230:233], v[132:135], v[64:79]
	ds_read_b128 v[214:217], v195 offset:57344
	ds_read_b128 v[230:233], v209 offset:57344
	v_exp_f32_e32 v150, v150
	v_add_f32_e32 v164, v146, v164
	v_exp_f32_e32 v151, v151
	v_add_f32_e32 v164, v147, v164
	v_exp_f32_e32 v144, v144
	v_add_f32_e32 v164, v154, v164
	s_waitcnt lgkmcnt(1)
	v_mfma_f32_32x32x16_bf16 v[80:95], v[214:217], v[128:131], v[80:95]
	v_exp_f32_e32 v145, v145
	v_add_f32_e32 v164, v155, v164
	v_add_f32_e32 v164, v150, v164
	v_add_f32_e32 v164, v151, v164
	v_add_f32_e32 v164, v144, v164
	v_add_f32_e32 v219, v145, v164
	v_mov_b32_e32 v220, v219
	s_waitcnt lgkmcnt(0)
	v_mfma_f32_32x32x16_bf16 v[64:79], v[230:233], v[128:131], v[64:79]
	ds_read_b128 v[214:217], v193 offset:57344
	ds_read_b128 v[230:233], v208 offset:57344
	v_permlane32_swap_b32_e32 v219, v220
	s_waitcnt lgkmcnt(1)
	v_mfma_f32_32x32x16_bf16 v[80:95], v[214:217], v[124:127], v[80:95]
	s_waitcnt lgkmcnt(0)
	v_mfma_f32_32x32x16_bf16 v[64:79], v[230:233], v[124:127], v[64:79]
	ds_read_b128 v[214:217], v192 offset:57344
	ds_read_b128 v[230:233], v206 offset:57344
	s_waitcnt lgkmcnt(1)
	v_mfma_f32_32x32x16_bf16 v[80:95], v[214:217], v[120:123], v[80:95]
	s_waitcnt lgkmcnt(0)
	v_mfma_f32_32x32x16_bf16 v[64:79], v[230:233], v[120:123], v[64:79]
	ds_read_b128 v[214:217], v186 offset:57344
	ds_read_b128 v[230:233], v205 offset:57344
	s_waitcnt lgkmcnt(1)
	v_mfma_f32_32x32x16_bf16 v[80:95], v[214:217], v[116:119], v[80:95]
	s_waitcnt lgkmcnt(0)
	v_mfma_f32_32x32x16_bf16 v[64:79], v[230:233], v[116:119], v[64:79]
	ds_read_b128 v[214:217], v189 offset:57344
	ds_read_b128 v[230:233], v204 offset:57344
	s_waitcnt lgkmcnt(1)
	v_mfma_f32_32x32x16_bf16 v[80:95], v[214:217], v[112:115], v[80:95]
	s_waitcnt lgkmcnt(0)
	v_mfma_f32_32x32x16_bf16 v[64:79], v[230:233], v[112:115], v[64:79]
	ds_read_b128 v[214:217], v190 offset:57344
	ds_read_b128 v[230:233], v203 offset:57344
	s_waitcnt lgkmcnt(1)
	v_mfma_f32_32x32x16_bf16 v[80:95], v[214:217], v[108:111], v[80:95]
	s_waitcnt lgkmcnt(0)
	v_mfma_f32_32x32x16_bf16 v[64:79], v[230:233], v[108:111], v[64:79]
	ds_read_b128 v[214:217], v188 offset:57344
	ds_read_b128 v[230:233], v202 offset:57344
	s_waitcnt lgkmcnt(1)
	v_mfma_f32_32x32x16_bf16 v[80:95], v[214:217], v[104:107], v[80:95]
	s_waitcnt lgkmcnt(0)
	v_mfma_f32_32x32x16_bf16 v[64:79], v[230:233], v[104:107], v[64:79]
	ds_read_b128 v[214:217], v199 offset:57344
	ds_read_b128 v[230:233], v201 offset:57344
	s_waitcnt lgkmcnt(1)
	v_mfma_f32_32x32x16_bf16 v[80:95], v[214:217], v[100:103], v[80:95]
	s_waitcnt lgkmcnt(0)
	v_mfma_f32_32x32x16_bf16 v[64:79], v[230:233], v[100:103], v[64:79]
	ds_read_b128 v[214:217], v198 offset:57344
	ds_read_b128 v[230:233], v200 offset:57344
	v_cvt_pk_bf16_f32 v164, v165, v224
	v_cvt_pk_bf16_f32 v165, v166, v225
	v_cvt_pk_bf16_f32 v166, v223, v226
	v_cvt_pk_bf16_f32 v167, v167, v222
	s_nop 0
	v_permlane32_swap_b32_e32 v164, v166
	s_waitcnt lgkmcnt(1)
	v_mfma_f32_32x32x16_bf16 v[80:95], v[214:217], v[96:99], v[80:95]
	v_cvt_pk_bf16_f32 v214, v172, v174
	v_cvt_pk_bf16_f32 v215, v173, v175
	v_cvt_pk_bf16_f32 v216, v160, v162
	v_cvt_pk_bf16_f32 v217, v161, v163
	v_cvt_pk_bf16_f32 v222, v158, v159
	v_cvt_pk_bf16_f32 v223, v156, v157
	v_cvt_pk_bf16_f32 v224, v152, v153
	s_waitcnt lgkmcnt(0)
	v_mfma_f32_32x32x16_bf16 v[64:79], v[230:233], v[96:99], v[64:79]
	v_cvt_pk_bf16_f32 v225, v148, v149
	v_cvt_pk_bf16_f32 v230, v146, v147
	v_cvt_pk_bf16_f32 v231, v154, v155
	v_cvt_pk_bf16_f32 v232, v150, v151
	v_cvt_pk_bf16_f32 v233, v144, v145
	v_permlane32_swap_b32_e32 v165, v167
	v_permlane32_swap_b32_e32 v214, v216
	v_permlane32_swap_b32_e32 v215, v217
	v_permlane32_swap_b32_e32 v222, v224
	v_permlane32_swap_b32_e32 v223, v225
	v_permlane32_swap_b32_e32 v230, v232
	v_permlane32_swap_b32_e32 v231, v233
	v_lshl_add_u64 v[172:173], s[44:45], 0, v[170:171]
	s_mov_b32 s2, 0x4bf80000
	v_add_co_u32_e32 v148, vcc, s2, v172
	s_mov_b32 s2, 0x4bfa0000
	s_nop 0
	v_addc_co_u32_e32 v149, vcc, 0, v173, vcc
	v_add_co_u32_e32 v152, vcc, s2, v172
	v_lshl_add_u64 v[174:175], s[44:45], 0, v[168:169]
	s_nop 0
	v_addc_co_u32_e32 v153, vcc, 0, v173, vcc
	global_load_dwordx4 v[144:147], v[148:149], off offset:256
	s_nop 0
	global_load_dwordx4 v[148:151], v[148:149], off
	s_nop 0
	global_load_dwordx4 v[156:159], v[152:153], off offset:256
	s_nop 0
	global_load_dwordx4 v[152:155], v[152:153], off
	s_mov_b32 s2, 0x45404000
	v_add_co_u32_e32 v160, vcc, s2, v174
	s_nop 1
	v_addc_co_u32_e32 v161, vcc, 0, v175, vcc
	global_load_dwordx4 v[160:163], v[160:161], off
	ds_read_b64_tr_b16 v[238:239], v182 offset:0
	ds_read_b64_tr_b16 v[240:241], v182 offset:0x800
	ds_read_b64_tr_b16 v[242:243], v182 offset:0x200
	ds_read_b64_tr_b16 v[244:245], v182 offset:0xa00
	ds_read_b64_tr_b16 v[246:247], v182 offset:0x400
	ds_read_b64_tr_b16 v[248:249], v182 offset:0xc00
	ds_read_b64_tr_b16 v[250:251], v182 offset:0x600
	ds_read_b64_tr_b16 v[252:253], v182 offset:0xe00
	s_waitcnt lgkmcnt(6)
	s_nop 0
	v_mfma_f32_32x32x16_bf16 v[0:15], v[164:167], v[238:241], v[0:15]
	ds_read_b64_tr_b16 v[238:239], v182 offset:0x1000
	ds_read_b64_tr_b16 v[240:241], v182 offset:0x1800
	s_waitcnt lgkmcnt(6)
	v_mfma_f32_32x32x16_bf16 v[48:63], v[164:167], v[242:245], v[48:63]
	ds_read_b64_tr_b16 v[242:243], v182 offset:0x1200
	ds_read_b64_tr_b16 v[244:245], v182 offset:0x1a00
	s_waitcnt lgkmcnt(6)
	v_mfma_f32_32x32x16_bf16 v[32:47], v[164:167], v[246:249], v[32:47]
	ds_read_b64_tr_b16 v[246:247], v182 offset:0x1400
	ds_read_b64_tr_b16 v[248:249], v182 offset:0x1c00
	s_waitcnt lgkmcnt(6)
	v_mfma_f32_32x32x16_bf16 v[16:31], v[164:167], v[250:253], v[16:31]
	ds_read_b64_tr_b16 v[250:251], v182 offset:0x1600
	ds_read_b64_tr_b16 v[252:253], v182 offset:0x1e00
	s_waitcnt lgkmcnt(6)
	v_mfma_f32_32x32x16_bf16 v[0:15], v[214:217], v[238:241], v[0:15]
	ds_read_b64_tr_b16 v[238:239], v182 offset:0x2000
	ds_read_b64_tr_b16 v[240:241], v182 offset:0x2800
	v_max_f32_e32 v164, v81, v81
	v_max_f32_e32 v165, v80, v80
	v_max_f32_e32 v164, v165, v164
	v_max3_f32 v164, v164, v82, v83
	v_max3_f32 v164, v164, v84, v85
	v_max3_f32 v164, v164, v86, v87
	v_max3_f32 v164, v164, v88, v89
	v_max3_f32 v164, v164, v90, v91
	s_waitcnt lgkmcnt(6)
	v_mfma_f32_32x32x16_bf16 v[48:63], v[214:217], v[242:245], v[48:63]
	ds_read_b64_tr_b16 v[242:243], v182 offset:0x2200
	ds_read_b64_tr_b16 v[244:245], v182 offset:0x2a00
	s_waitcnt lgkmcnt(6)
	v_mfma_f32_32x32x16_bf16 v[32:47], v[214:217], v[246:249], v[32:47]
	ds_read_b64_tr_b16 v[246:247], v182 offset:0x2400
	ds_read_b64_tr_b16 v[248:249], v182 offset:0x2c00
	v_max3_f32 v164, v164, v92, v93
	v_max3_f32 v164, v164, v94, v95
	v_max3_f32 v164, v164, v64, v65
	v_max3_f32 v164, v164, v66, v67
	v_max3_f32 v164, v164, v68, v69
	v_max3_f32 v164, v164, v70, v71
	v_max3_f32 v164, v164, v72, v73
	v_max3_f32 v164, v164, v74, v75
	s_waitcnt lgkmcnt(6)
	v_mfma_f32_32x32x16_bf16 v[16:31], v[214:217], v[250:253], v[16:31]
	ds_read_b64_tr_b16 v[250:251], v182 offset:0x2600
	ds_read_b64_tr_b16 v[252:253], v182 offset:0x2e00
	s_waitcnt lgkmcnt(6)
	v_mfma_f32_32x32x16_bf16 v[0:15], v[222:225], v[238:241], v[0:15]
	ds_read_b64_tr_b16 v[238:239], v182 offset:0x3000
	ds_read_b64_tr_b16 v[240:241], v182 offset:0x3800
	v_max3_f32 v164, v164, v76, v77
	v_max3_f32 v164, v164, v78, v79
	v_mov_b32_e32 v165, v164
	s_nop 1
	v_permlane32_swap_b32_e32 v164, v165
	v_max_f32_e32 v165, v165, v165
	v_max_f32_e32 v164, v164, v164
	v_max_f32_e32 v164, v164, v165
	s_waitcnt lgkmcnt(6)
	v_mfma_f32_32x32x16_bf16 v[48:63], v[222:225], v[242:245], v[48:63]
	ds_read_b64_tr_b16 v[242:243], v182 offset:0x3200
	ds_read_b64_tr_b16 v[244:245], v182 offset:0x3a00
	s_waitcnt lgkmcnt(6)
	v_mfma_f32_32x32x16_bf16 v[32:47], v[222:225], v[246:249], v[32:47]
	ds_read_b64_tr_b16 v[246:247], v182 offset:0x3400
	ds_read_b64_tr_b16 v[248:249], v182 offset:0x3c00
	v_sub_f32_e32 v165, v164, v207
	v_cmp_ge_f32_e32 vcc, s46, v165
	v_max_f32_e32 v165, v207, v207
	v_max_f32_e32 v164, v165, v164
	v_sub_f32_e32 v165, v207, v164
	v_mul_f32_e32 v165, 0x3dd53b94, v165
	v_exp_f32_e32 v165, v165
	s_cmp_eq_u64 vcc, exec
	s_cselect_b64 s[38:39], -1, 0
	s_waitcnt lgkmcnt(6)
	v_mfma_f32_32x32x16_bf16 v[16:31], v[222:225], v[250:253], v[16:31]
	ds_read_b64_tr_b16 v[250:251], v182 offset:0x3600
	ds_read_b64_tr_b16 v[252:253], v182 offset:0x3e00
	s_waitcnt lgkmcnt(6)
	v_mfma_f32_32x32x16_bf16 v[0:15], v[230:233], v[238:241], v[0:15]
	s_waitcnt lgkmcnt(0)
	s_barrier
	v_mfma_f32_32x32x16_bf16 v[48:63], v[230:233], v[242:245], v[48:63]
	s_waitcnt vmcnt(0)
	v_cndmask_b32_e64 v221, v165, 1.0, s[38:39]
	v_cmp_gt_f32_e32 vcc, 1.0, v221
	s_waitcnt vmcnt(4)
	ds_write_b128 v183, v[144:147]
	s_waitcnt vmcnt(2)
	ds_write_b128 v184, v[156:159]
	v_mfma_f32_32x32x16_bf16 v[32:47], v[230:233], v[246:249], v[32:47]
	ds_write_b128 v185, v[148:151] offset:32768
	s_waitcnt vmcnt(1)
	ds_write_b128 v187, v[152:155] offset:32768
	s_waitcnt vmcnt(0)
	ds_write_b128 v191, v[160:163] offset:32768
	v_mfma_f32_32x32x16_bf16 v[16:31], v[230:233], v[250:253], v[16:31]
	s_cbranch_vccz .LBB0_1139
	s_and_saveexec_b64 s[2:3], s[36:37]
	ds_write_b32 v179, v221 offset:128
	s_or_b64 exec, exec, s[2:3]
	s_waitcnt lgkmcnt(0)
	v_add_u32_e32 v156, s14, v178
	ds_read_b128 v[144:147], v156 offset:224
	ds_read_b128 v[148:151], v156 offset:192
	ds_read_b128 v[152:155], v156 offset:160
	ds_read_b128 v[156:159], v156 offset:128
	s_waitcnt lgkmcnt(3)
	v_pk_mul_f32 v[12:13], v[12:13], v[144:145]
	s_waitcnt lgkmcnt(2)
	v_pk_mul_f32 v[8:9], v[8:9], v[148:149]
	s_waitcnt lgkmcnt(1)
	v_pk_mul_f32 v[4:5], v[4:5], v[152:153]
	v_pk_mul_f32 v[14:15], v[14:15], v[146:147]
	v_pk_mul_f32 v[10:11], v[10:11], v[150:151]
	v_pk_mul_f32 v[6:7], v[6:7], v[154:155]
	s_waitcnt lgkmcnt(0)
	v_pk_mul_f32 v[2:3], v[2:3], v[158:159]
	v_pk_mul_f32 v[0:1], v[0:1], v[156:157]
	v_pk_mul_f32 v[60:61], v[60:61], v[144:145]
	v_pk_mul_f32 v[56:57], v[56:57], v[148:149]
	v_pk_mul_f32 v[52:53], v[52:53], v[152:153]
	v_pk_mul_f32 v[62:63], v[62:63], v[146:147]
	v_pk_mul_f32 v[58:59], v[58:59], v[150:151]
	v_pk_mul_f32 v[54:55], v[54:55], v[154:155]
	v_pk_mul_f32 v[50:51], v[50:51], v[158:159]
	v_pk_mul_f32 v[48:49], v[48:49], v[156:157]
	v_pk_mul_f32 v[44:45], v[44:45], v[144:145]
	v_pk_mul_f32 v[40:41], v[40:41], v[148:149]
	v_pk_mul_f32 v[36:37], v[36:37], v[152:153]
	v_pk_mul_f32 v[46:47], v[46:47], v[146:147]
	v_pk_mul_f32 v[42:43], v[42:43], v[150:151]
	v_pk_mul_f32 v[38:39], v[38:39], v[154:155]
	v_pk_mul_f32 v[34:35], v[34:35], v[158:159]
	v_pk_mul_f32 v[32:33], v[32:33], v[156:157]
	v_pk_mul_f32 v[28:29], v[28:29], v[144:145]
	v_pk_mul_f32 v[24:25], v[24:25], v[148:149]
	v_pk_mul_f32 v[20:21], v[20:21], v[152:153]
	v_pk_mul_f32 v[30:31], v[30:31], v[146:147]
	v_pk_mul_f32 v[26:27], v[26:27], v[150:151]
	v_pk_mul_f32 v[22:23], v[22:23], v[154:155]
	v_pk_mul_f32 v[18:19], v[18:19], v[158:159]
	v_pk_mul_f32 v[16:17], v[16:17], v[156:157]
.LBB0_1139:
	v_cndmask_b32_e64 v207, v164, v207, s[38:39]
	v_mul_f32_e32 v160, 0xbdd53b94, v207
	v_fmamk_f32 v80, v80, 0x3dd53b94, v160
	v_fmamk_f32 v81, v81, 0x3dd53b94, v160
	v_fmamk_f32 v82, v82, 0x3dd53b94, v160
	v_fmamk_f32 v83, v83, 0x3dd53b94, v160
	v_fmamk_f32 v84, v84, 0x3dd53b94, v160
	v_fmamk_f32 v85, v85, 0x3dd53b94, v160
	v_fmamk_f32 v86, v86, 0x3dd53b94, v160
	v_fmamk_f32 v87, v87, 0x3dd53b94, v160
	v_fmamk_f32 v88, v88, 0x3dd53b94, v160
	v_fmamk_f32 v89, v89, 0x3dd53b94, v160
	v_fmamk_f32 v90, v90, 0x3dd53b94, v160
	v_fmamk_f32 v91, v91, 0x3dd53b94, v160
	v_fmamk_f32 v92, v92, 0x3dd53b94, v160
	v_fmamk_f32 v93, v93, 0x3dd53b94, v160
	v_fmamk_f32 v94, v94, 0x3dd53b94, v160
	v_fmamk_f32 v95, v95, 0x3dd53b94, v160
	v_fmamk_f32 v227, v68, 0x3dd53b94, v160
	v_fmamk_f32 v164, v71, 0x3dd53b94, v160
	v_fmamk_f32 v165, v72, 0x3dd53b94, v160
	v_fmamk_f32 v238, v77, 0x3dd53b94, v160
	v_fmamk_f32 v223, v64, 0x3dd53b94, v160
	v_fmamk_f32 v224, v65, 0x3dd53b94, v160
	v_fmamk_f32 v225, v66, 0x3dd53b94, v160
	v_fmamk_f32 v226, v67, 0x3dd53b94, v160
	v_fmamk_f32 v162, v69, 0x3dd53b94, v160
	v_fmamk_f32 v163, v70, 0x3dd53b94, v160
	v_fmamk_f32 v166, v73, 0x3dd53b94, v160
	v_fmamk_f32 v167, v74, 0x3dd53b94, v160
	v_fmamk_f32 v222, v75, 0x3dd53b94, v160
	v_fmamk_f32 v161, v76, 0x3dd53b94, v160
	v_exp_f32_e32 v157, v80
	v_exp_f32_e32 v159, v81
	v_exp_f32_e32 v155, v82
	v_exp_f32_e32 v158, v83
	v_exp_f32_e32 v154, v84
	v_exp_f32_e32 v156, v85
	v_exp_f32_e32 v152, v86
	v_exp_f32_e32 v153, v87
	v_exp_f32_e32 v149, v88
	v_exp_f32_e32 v151, v89
	v_exp_f32_e32 v148, v90
	v_exp_f32_e32 v150, v91
	v_exp_f32_e32 v145, v92
	v_exp_f32_e32 v147, v93
	v_exp_f32_e32 v144, v94
	v_exp_f32_e32 v146, v95
	v_fmamk_f32 v239, v78, 0x3dd53b94, v160
	v_fmac_f32_e32 v160, 0x3dd53b94, v79
	s_waitcnt lgkmcnt(0)
	s_barrier
	ds_read_b128 v[64:67], v194 offset:32768
	ds_read_b128 v[68:71], v194 offset:45056
	ds_read_b128 v[214:217], v197 offset:32768
	ds_read_b128 v[230:233], v197 offset:45056
	v_exp_f32_e32 v223, v223
	v_exp_f32_e32 v224, v224
	s_waitcnt lgkmcnt(3)
	v_mfma_f32_32x32x16_bf16 v[80:95], v[64:67], v[140:143], 0
	v_exp_f32_e32 v225, v225
	v_exp_f32_e32 v226, v226
	v_exp_f32_e32 v162, v162
	v_exp_f32_e32 v163, v163
	v_exp_f32_e32 v234, v167
	v_exp_f32_e32 v235, v222
	v_exp_f32_e32 v161, v161
	s_waitcnt lgkmcnt(2)
	v_mfma_f32_32x32x16_bf16 v[64:79], v[68:71], v[140:143], 0
	v_exp_f32_e32 v240, v238
	v_exp_f32_e32 v239, v239
	v_exp_f32_e32 v160, v160
	s_waitcnt lgkmcnt(0)
	v_mfma_f32_32x32x16_bf16 v[64:79], v[230:233], v[136:139], v[64:79]
	v_mfma_f32_32x32x16_bf16 v[80:95], v[214:217], v[136:139], v[80:95]
	ds_read_b128 v[214:217], v196 offset:32768
	ds_read_b128 v[230:233], v196 offset:45056
	s_waitcnt lgkmcnt(0)
	v_mfma_f32_32x32x16_bf16 v[64:79], v[230:233], v[132:135], v[64:79]
	v_mfma_f32_32x32x16_bf16 v[80:95], v[214:217], v[132:135], v[80:95]
	ds_read_b128 v[214:217], v195 offset:32768
	ds_read_b128 v[230:233], v195 offset:45056
	s_waitcnt lgkmcnt(0)
	v_mfma_f32_32x32x16_bf16 v[64:79], v[230:233], v[128:131], v[64:79]
	v_mfma_f32_32x32x16_bf16 v[80:95], v[214:217], v[128:131], v[80:95]
	ds_read_b128 v[214:217], v193 offset:32768
	ds_read_b128 v[230:233], v193 offset:45056
	s_waitcnt lgkmcnt(0)
	v_mfma_f32_32x32x16_bf16 v[64:79], v[230:233], v[124:127], v[64:79]
	v_mfma_f32_32x32x16_bf16 v[80:95], v[214:217], v[124:127], v[80:95]
	ds_read_b128 v[214:217], v192 offset:32768
	ds_read_b128 v[230:233], v192 offset:45056
	s_waitcnt lgkmcnt(0)
	v_mfma_f32_32x32x16_bf16 v[64:79], v[230:233], v[120:123], v[64:79]
	v_mfma_f32_32x32x16_bf16 v[80:95], v[214:217], v[120:123], v[80:95]
	ds_read_b128 v[214:217], v186 offset:32768
	ds_read_b128 v[230:233], v186 offset:45056
	s_waitcnt lgkmcnt(0)
	v_mfma_f32_32x32x16_bf16 v[64:79], v[230:233], v[116:119], v[64:79]
	v_mfma_f32_32x32x16_bf16 v[80:95], v[214:217], v[116:119], v[80:95]
	ds_read_b128 v[214:217], v189 offset:32768
	ds_read_b128 v[230:233], v189 offset:45056
	s_waitcnt lgkmcnt(0)
	v_mfma_f32_32x32x16_bf16 v[64:79], v[230:233], v[112:115], v[64:79]
	v_mfma_f32_32x32x16_bf16 v[80:95], v[214:217], v[112:115], v[80:95]
	ds_read_b128 v[214:217], v190 offset:32768
	ds_read_b128 v[230:233], v190 offset:45056
	s_waitcnt lgkmcnt(0)
	v_mfma_f32_32x32x16_bf16 v[64:79], v[230:233], v[108:111], v[64:79]
	v_mfma_f32_32x32x16_bf16 v[80:95], v[214:217], v[108:111], v[80:95]
	ds_read_b128 v[214:217], v188 offset:32768
	ds_read_b128 v[230:233], v188 offset:45056
	s_waitcnt lgkmcnt(0)
	v_mfma_f32_32x32x16_bf16 v[64:79], v[230:233], v[104:107], v[64:79]
	v_mfma_f32_32x32x16_bf16 v[80:95], v[214:217], v[104:107], v[80:95]
	ds_read_b128 v[214:217], v199 offset:32768
	ds_read_b128 v[230:233], v199 offset:45056
	s_waitcnt lgkmcnt(0)
	v_mfma_f32_32x32x16_bf16 v[64:79], v[230:233], v[100:103], v[64:79]
	v_mfma_f32_32x32x16_bf16 v[80:95], v[214:217], v[100:103], v[80:95]
	ds_read_b128 v[214:217], v198 offset:32768
	ds_read_b128 v[230:233], v198 offset:45056
	s_waitcnt lgkmcnt(0)
	v_mfma_f32_32x32x16_bf16 v[64:79], v[230:233], v[96:99], v[64:79]
	v_exp_f32_e32 v231, v164
	v_add_f32_e32 v164, 0, v157
	v_add_f32_e32 v164, v159, v164
	v_add_f32_e32 v164, v155, v164
	v_add_f32_e32 v164, v158, v164
	v_add_f32_e32 v164, v154, v164
	v_add_f32_e32 v164, v156, v164
	v_add_f32_e32 v164, v152, v164
	v_add_f32_e32 v164, v153, v164
	v_add_f32_e32 v164, v149, v164
	v_add_f32_e32 v164, v151, v164
	v_add_f32_e32 v164, v148, v164
	v_add_f32_e32 v164, v150, v164
	v_add_f32_e32 v164, v145, v164
	v_add_f32_e32 v164, v147, v164
	v_add_f32_e32 v164, v144, v164
	v_add_f32_e32 v164, v146, v164
	v_exp_f32_e32 v230, v227
	v_add_f32_e32 v164, v223, v164
	v_add_f32_e32 v164, v224, v164
	v_add_f32_e32 v164, v225, v164
	v_add_f32_e32 v164, v226, v164
	v_exp_f32_e32 v232, v165
	v_add_f32_e32 v164, v230, v164
	v_exp_f32_e32 v233, v166
	v_add_f32_e32 v164, v162, v164
	v_add_f32_e32 v164, v163, v164
	v_add_f32_e32 v164, v231, v164
	v_add_f32_e32 v164, v232, v164
	v_add_f32_e32 v164, v233, v164
	v_mfma_f32_32x32x16_bf16 v[80:95], v[214:217], v[96:99], v[80:95]
	v_add_f32_e32 v164, v234, v164
	v_add_f32_e32 v164, v235, v164
	v_add_f32_e32 v164, v161, v164
	v_add_f32_e32 v164, v240, v164
	v_add_f32_e32 v164, v239, v164
	v_add_f32_e32 v227, v160, v164
	v_mov_b32_e32 v238, v227
	v_cvt_pk_bf16_f32 v164, v157, v159
	v_cvt_pk_bf16_f32 v165, v155, v158
	v_cvt_pk_bf16_f32 v166, v154, v156
	v_cvt_pk_bf16_f32 v167, v152, v153
	s_nop 1
	v_permlane32_swap_b32_e32 v227, v238
	v_permlane32_swap_b32_e32 v164, v166
	v_permlane32_swap_b32_e32 v165, v167
	v_cvt_pk_bf16_f32 v214, v149, v151
	v_cvt_pk_bf16_f32 v215, v148, v150
	v_cvt_pk_bf16_f32 v216, v145, v147
	v_cvt_pk_bf16_f32 v217, v144, v146
	v_cvt_pk_bf16_f32 v222, v223, v224
	v_cvt_pk_bf16_f32 v223, v225, v226
	v_cvt_pk_bf16_f32 v224, v230, v162
	v_cvt_pk_bf16_f32 v225, v163, v231
	v_cvt_pk_bf16_f32 v230, v232, v233
	v_cvt_pk_bf16_f32 v231, v234, v235
	v_cvt_pk_bf16_f32 v232, v161, v240
	v_cvt_pk_bf16_f32 v233, v239, v160
	s_nop 0
	v_permlane32_swap_b32_e32 v214, v216
	v_permlane32_swap_b32_e32 v215, v217
	v_permlane32_swap_b32_e32 v222, v224
	v_permlane32_swap_b32_e32 v223, v225
	v_permlane32_swap_b32_e32 v230, v232
	v_permlane32_swap_b32_e32 v231, v233
	s_mov_b32 s2, 0x4bfc0000
	v_add_co_u32_e32 v148, vcc, s2, v172
	s_mov_b32 s2, 0x4bfe0000
	s_nop 0
	v_addc_co_u32_e32 v149, vcc, 0, v173, vcc
	v_add_co_u32_e32 v152, vcc, s2, v172
	s_mov_b32 s2, 0x45406000
	s_nop 0
	v_addc_co_u32_e32 v153, vcc, 0, v173, vcc
	global_load_dwordx4 v[144:147], v[148:149], off offset:256
	s_nop 0
	global_load_dwordx4 v[148:151], v[148:149], off
	s_nop 0
	global_load_dwordx4 v[156:159], v[152:153], off offset:256
	s_nop 0
	global_load_dwordx4 v[152:155], v[152:153], off
	v_add_co_u32_e32 v160, vcc, s2, v174
	s_nop 1
	v_addc_co_u32_e32 v161, vcc, 0, v175, vcc
	global_load_dwordx4 v[160:163], v[160:161], off
	ds_read_b64_tr_b16 v[172:173], v181 offset:0
	ds_read_b64_tr_b16 v[174:175], v181 offset:0x800
	ds_read_b64_tr_b16 v[240:241], v181 offset:0x200
	ds_read_b64_tr_b16 v[242:243], v181 offset:0xa00
	ds_read_b64_tr_b16 v[244:245], v181 offset:0x400
	ds_read_b64_tr_b16 v[246:247], v181 offset:0xc00
	ds_read_b64_tr_b16 v[248:249], v181 offset:0x600
	ds_read_b64_tr_b16 v[250:251], v181 offset:0xe00
	s_waitcnt lgkmcnt(6)
	s_nop 0
	v_mfma_f32_32x32x16_bf16 v[0:15], v[164:167], v[172:175], v[0:15]
	ds_read_b64_tr_b16 v[172:173], v181 offset:0x1000
	ds_read_b64_tr_b16 v[174:175], v181 offset:0x1800
	s_waitcnt lgkmcnt(6)
	v_mfma_f32_32x32x16_bf16 v[48:63], v[164:167], v[240:243], v[48:63]
	ds_read_b64_tr_b16 v[240:241], v181 offset:0x1200
	ds_read_b64_tr_b16 v[242:243], v181 offset:0x1a00
	s_waitcnt lgkmcnt(6)
	v_mfma_f32_32x32x16_bf16 v[32:47], v[164:167], v[244:247], v[32:47]
	ds_read_b64_tr_b16 v[244:245], v181 offset:0x1400
	ds_read_b64_tr_b16 v[246:247], v181 offset:0x1c00
	s_waitcnt lgkmcnt(6)
	v_mfma_f32_32x32x16_bf16 v[16:31], v[164:167], v[248:251], v[16:31]
	ds_read_b64_tr_b16 v[248:249], v181 offset:0x1600
	ds_read_b64_tr_b16 v[250:251], v181 offset:0x1e00
	s_waitcnt lgkmcnt(6)
	v_mfma_f32_32x32x16_bf16 v[0:15], v[214:217], v[172:175], v[0:15]
	ds_read_b64_tr_b16 v[172:173], v181 offset:0x2000
	ds_read_b64_tr_b16 v[174:175], v181 offset:0x2800
	v_max_f32_e32 v164, v81, v81
	v_max_f32_e32 v165, v80, v80
	v_max_f32_e32 v164, v165, v164
	v_max3_f32 v164, v164, v82, v83
	v_max3_f32 v164, v164, v84, v85
	v_max3_f32 v164, v164, v86, v87
	v_max3_f32 v164, v164, v88, v89
	v_max3_f32 v164, v164, v90, v91
	s_waitcnt lgkmcnt(6)
	v_mfma_f32_32x32x16_bf16 v[48:63], v[214:217], v[240:243], v[48:63]
	ds_read_b64_tr_b16 v[240:241], v181 offset:0x2200
	ds_read_b64_tr_b16 v[242:243], v181 offset:0x2a00
	s_waitcnt lgkmcnt(6)
	v_mfma_f32_32x32x16_bf16 v[32:47], v[214:217], v[244:247], v[32:47]
	ds_read_b64_tr_b16 v[244:245], v181 offset:0x2400
	ds_read_b64_tr_b16 v[246:247], v181 offset:0x2c00
	v_max3_f32 v164, v164, v92, v93
	v_max3_f32 v164, v164, v94, v95
	v_max3_f32 v164, v164, v64, v65
	v_max3_f32 v164, v164, v66, v67
	v_max3_f32 v164, v164, v68, v69
	v_max3_f32 v164, v164, v70, v71
	v_max3_f32 v164, v164, v72, v73
	v_max3_f32 v164, v164, v74, v75
	s_waitcnt lgkmcnt(6)
	v_mfma_f32_32x32x16_bf16 v[16:31], v[214:217], v[248:251], v[16:31]
	ds_read_b64_tr_b16 v[248:249], v181 offset:0x2600
	ds_read_b64_tr_b16 v[250:251], v181 offset:0x2e00
	s_waitcnt lgkmcnt(6)
	v_mfma_f32_32x32x16_bf16 v[0:15], v[222:225], v[172:175], v[0:15]
	ds_read_b64_tr_b16 v[172:173], v181 offset:0x3000
	ds_read_b64_tr_b16 v[174:175], v181 offset:0x3800
	v_max3_f32 v164, v164, v76, v77
	v_max3_f32 v164, v164, v78, v79
	v_mov_b32_e32 v165, v164
	s_nop 1
	v_permlane32_swap_b32_e32 v164, v165
	v_max_f32_e32 v165, v165, v165
	v_max_f32_e32 v164, v164, v164
	v_max_f32_e32 v164, v164, v165
	s_waitcnt lgkmcnt(6)
	v_mfma_f32_32x32x16_bf16 v[48:63], v[222:225], v[240:243], v[48:63]
	ds_read_b64_tr_b16 v[240:241], v181 offset:0x3200
	ds_read_b64_tr_b16 v[242:243], v181 offset:0x3a00
	s_waitcnt lgkmcnt(6)
	v_mfma_f32_32x32x16_bf16 v[32:47], v[222:225], v[244:247], v[32:47]
	ds_read_b64_tr_b16 v[244:245], v181 offset:0x3400
	ds_read_b64_tr_b16 v[246:247], v181 offset:0x3c00
	v_sub_f32_e32 v165, v164, v207
	v_cmp_ge_f32_e32 vcc, s46, v165
	v_max_f32_e32 v165, v207, v207
	v_max_f32_e32 v165, v165, v164
	v_sub_f32_e32 v164, v207, v165
	v_mul_f32_e32 v164, 0x3dd53b94, v164
	v_exp_f32_e32 v164, v164
	s_cmp_eq_u64 vcc, exec
	s_cselect_b64 s[38:39], -1, 0
	s_waitcnt lgkmcnt(6)
	v_mfma_f32_32x32x16_bf16 v[16:31], v[222:225], v[248:251], v[16:31]
	ds_read_b64_tr_b16 v[248:249], v181 offset:0x3600
	ds_read_b64_tr_b16 v[250:251], v181 offset:0x3e00
	s_waitcnt lgkmcnt(6)
	v_mfma_f32_32x32x16_bf16 v[0:15], v[230:233], v[172:175], v[0:15]
	s_waitcnt lgkmcnt(0)
	s_barrier
	v_mfma_f32_32x32x16_bf16 v[48:63], v[230:233], v[240:243], v[48:63]
	s_waitcnt vmcnt(0)
	v_cndmask_b32_e64 v164, v164, 1.0, s[38:39]
	v_cmp_gt_f32_e32 vcc, 1.0, v164
	s_waitcnt vmcnt(4)
	ds_write_b128 v183, v[144:147] offset:16384
	s_waitcnt vmcnt(2)
	ds_write_b128 v184, v[156:159] offset:16384
	v_mfma_f32_32x32x16_bf16 v[32:47], v[230:233], v[244:247], v[32:47]
	ds_write_b128 v185, v[148:151] offset:57344
	s_waitcnt vmcnt(1)
	ds_write_b128 v187, v[152:155] offset:57344
	s_waitcnt vmcnt(0)
	ds_write_b128 v191, v[160:163] offset:57344
	v_mfma_f32_32x32x16_bf16 v[16:31], v[230:233], v[248:251], v[16:31]
	s_cbranch_vccz .LBB0_1143
	s_and_saveexec_b64 s[2:3], s[36:37]
	ds_write_b32 v179, v164 offset:128
	s_or_b64 exec, exec, s[2:3]
	s_waitcnt lgkmcnt(0)
	v_add_u32_e32 v156, s14, v178
	ds_read_b128 v[144:147], v156 offset:224
	ds_read_b128 v[148:151], v156 offset:192
	ds_read_b128 v[152:155], v156 offset:160
	ds_read_b128 v[156:159], v156 offset:128
	s_waitcnt lgkmcnt(3)
	v_pk_mul_f32 v[12:13], v[12:13], v[144:145]
	s_waitcnt lgkmcnt(2)
	v_pk_mul_f32 v[8:9], v[8:9], v[148:149]
	s_waitcnt lgkmcnt(1)
	v_pk_mul_f32 v[4:5], v[4:5], v[152:153]
	v_pk_mul_f32 v[14:15], v[14:15], v[146:147]
	v_pk_mul_f32 v[10:11], v[10:11], v[150:151]
	v_pk_mul_f32 v[6:7], v[6:7], v[154:155]
	s_waitcnt lgkmcnt(0)
	v_pk_mul_f32 v[2:3], v[2:3], v[158:159]
	v_pk_mul_f32 v[0:1], v[0:1], v[156:157]
	v_pk_mul_f32 v[60:61], v[60:61], v[144:145]
	v_pk_mul_f32 v[56:57], v[56:57], v[148:149]
	v_pk_mul_f32 v[52:53], v[52:53], v[152:153]
	v_pk_mul_f32 v[62:63], v[62:63], v[146:147]
	v_pk_mul_f32 v[58:59], v[58:59], v[150:151]
	v_pk_mul_f32 v[54:55], v[54:55], v[154:155]
	v_pk_mul_f32 v[50:51], v[50:51], v[158:159]
	v_pk_mul_f32 v[48:49], v[48:49], v[156:157]
	v_pk_mul_f32 v[44:45], v[44:45], v[144:145]
	v_pk_mul_f32 v[40:41], v[40:41], v[148:149]
	v_pk_mul_f32 v[36:37], v[36:37], v[152:153]
	v_pk_mul_f32 v[46:47], v[46:47], v[146:147]
	v_pk_mul_f32 v[42:43], v[42:43], v[150:151]
	v_pk_mul_f32 v[38:39], v[38:39], v[154:155]
	v_pk_mul_f32 v[34:35], v[34:35], v[158:159]
	v_pk_mul_f32 v[32:33], v[32:33], v[156:157]
	v_pk_mul_f32 v[28:29], v[28:29], v[144:145]
	v_pk_mul_f32 v[24:25], v[24:25], v[148:149]
	v_pk_mul_f32 v[20:21], v[20:21], v[152:153]
	v_pk_mul_f32 v[30:31], v[30:31], v[146:147]
	v_pk_mul_f32 v[26:27], v[26:27], v[150:151]
	v_pk_mul_f32 v[22:23], v[22:23], v[154:155]
	v_pk_mul_f32 v[18:19], v[18:19], v[158:159]
	v_pk_mul_f32 v[16:17], v[16:17], v[156:157]
